# GEMM1a main loop without the 16 per-segment s_setprio toggles; on top of v067
# speedup vs baseline: 1.0004x; 1.0004x over previous
.LBB0_101:
	ds_read_b128 v[142:145], v161
	ds_read_b128 v[146:149], v234
	ds_read_b128 v[150:153], v161 offset:2048
	ds_read_b128 v[154:157], v234 offset:2048
	ds_read_b128 v[164:167], v162
	ds_read_b128 v[168:171], v235
	ds_read_b128 v[172:175], v162 offset:2048
	ds_read_b128 v[176:179], v235 offset:2048
	s_add_u32 s48, s46, 0xfff00080
	s_addc_u32 s49, s47, -1
	s_cmp_eq_u32 s77, 60
	s_cselect_b32 s51, s5, s49
	s_cselect_b32 s50, s29, s48
	s_cselect_b32 s49, s27, s76
	s_cselect_b32 s48, s74, s75
	v_lshl_add_u64 v[214:215], s[46:47], 0, v[134:135]
	s_add_i32 m0, s19, 0xc000
	ds_read_b128 v[180:183], v163
	ds_read_b128 v[184:187], v232
	ds_read_b128 v[188:191], v163 offset:2048
	ds_read_b128 v[192:195], v232 offset:2048
	ds_read_b128 v[196:199], v163 offset:4096
	ds_read_b128 v[200:203], v232 offset:4096
	ds_read_b128 v[204:207], v163 offset:6144
	ds_read_b128 v[208:211], v232 offset:6144
	global_load_lds_dwordx4 v[214:215], off
	v_lshl_add_u64 v[214:215], s[46:47], 0, v[136:137]
	s_add_i32 m0, s19, 0xe000
	s_nop 0
	global_load_lds_dwordx4 v[214:215], off
	s_waitcnt vmcnt(8)
	s_waitcnt lgkmcnt(0)
	s_barrier
	s_waitcnt lgkmcnt(0)
	v_mfma_f32_16x16x32_bf16 v[124:127], v[142:145], v[180:183], v[124:127]
	v_mfma_f32_16x16x32_bf16 v[120:123], v[150:153], v[180:183], v[120:123]
	v_mfma_f32_16x16x32_bf16 v[116:119], v[142:145], v[188:191], v[116:119]
	v_mfma_f32_16x16x32_bf16 v[112:115], v[150:153], v[188:191], v[112:115]
	v_mfma_f32_16x16x32_bf16 v[100:103], v[142:145], v[196:199], v[100:103]
	v_mfma_f32_16x16x32_bf16 v[96:99], v[150:153], v[196:199], v[96:99]
	v_mfma_f32_16x16x32_bf16 v[84:87], v[142:145], v[204:207], v[84:87]
	v_mfma_f32_16x16x32_bf16 v[80:83], v[150:153], v[204:207], v[80:83]
	v_mfma_f32_16x16x32_bf16 v[124:127], v[146:149], v[184:187], v[124:127]
	v_mfma_f32_16x16x32_bf16 v[120:123], v[154:157], v[184:187], v[120:123]
	v_mfma_f32_16x16x32_bf16 v[116:119], v[146:149], v[192:195], v[116:119]
	v_mfma_f32_16x16x32_bf16 v[112:115], v[154:157], v[192:195], v[112:115]
	v_mfma_f32_16x16x32_bf16 v[100:103], v[146:149], v[200:203], v[100:103]
	v_mfma_f32_16x16x32_bf16 v[96:99], v[154:157], v[200:203], v[96:99]
	v_mfma_f32_16x16x32_bf16 v[84:87], v[146:149], v[208:211], v[84:87]
	v_mfma_f32_16x16x32_bf16 v[80:83], v[154:157], v[208:211], v[80:83]
	v_mfma_f32_16x16x32_bf16 v[108:111], v[164:167], v[180:183], v[108:111]
	v_mfma_f32_16x16x32_bf16 v[104:107], v[172:175], v[180:183], v[104:107]
	v_mfma_f32_16x16x32_bf16 v[92:95], v[164:167], v[188:191], v[92:95]
	v_mfma_f32_16x16x32_bf16 v[88:91], v[172:175], v[188:191], v[88:91]
	v_mfma_f32_16x16x32_bf16 v[76:79], v[164:167], v[196:199], v[76:79]
	v_mfma_f32_16x16x32_bf16 v[72:75], v[172:175], v[196:199], v[72:75]
	v_mfma_f32_16x16x32_bf16 v[68:71], v[164:167], v[204:207], v[68:71]
	v_mfma_f32_16x16x32_bf16 v[64:67], v[172:175], v[204:207], v[64:67]
	v_mfma_f32_16x16x32_bf16 v[108:111], v[168:171], v[184:187], v[108:111]
	v_mfma_f32_16x16x32_bf16 v[104:107], v[176:179], v[184:187], v[104:107]
	v_mfma_f32_16x16x32_bf16 v[92:95], v[168:171], v[192:195], v[92:95]
	v_mfma_f32_16x16x32_bf16 v[88:91], v[176:179], v[192:195], v[88:91]
	v_mfma_f32_16x16x32_bf16 v[76:79], v[168:171], v[200:203], v[76:79]
	v_mfma_f32_16x16x32_bf16 v[72:75], v[176:179], v[200:203], v[72:75]
	v_mfma_f32_16x16x32_bf16 v[68:71], v[168:171], v[208:211], v[68:71]
	v_mfma_f32_16x16x32_bf16 v[64:67], v[176:179], v[208:211], v[64:67]
	s_barrier
	s_add_i32 s78, s68, s58
	v_lshl_add_u64 v[214:215], s[48:49], 0, v[128:129]
	s_mov_b32 m0, s78
	ds_read_b128 v[180:183], v163 offset:16384
	ds_read_b128 v[184:187], v232 offset:16384
	ds_read_b128 v[188:191], v163 offset:18432
	ds_read_b128 v[192:195], v232 offset:18432
	ds_read_b128 v[196:199], v163 offset:20480
	ds_read_b128 v[200:203], v232 offset:20480
	ds_read_b128 v[204:207], v163 offset:22528
	ds_read_b128 v[208:211], v232 offset:22528
	global_load_lds_dwordx4 v[214:215], off
	s_add_i32 m0, s78, 0x2000
	s_add_u32 s78, s48, 0x100000
	v_lshl_add_u64 v[216:217], s[48:49], 0, v[130:131]
	s_addc_u32 s79, s49, 0
	s_add_i32 s80, s69, s58
	global_load_lds_dwordx4 v[216:217], off
	v_lshl_add_u64 v[218:219], s[78:79], 0, v[128:129]
	s_mov_b32 m0, s80
	v_lshl_add_u64 v[220:221], s[50:51], 0, v[130:131]
	global_load_lds_dwordx4 v[218:219], off
	v_lshl_add_u64 v[218:219], s[78:79], 0, v[130:131]
	s_add_i32 m0, s80, 0x2000
	s_nop 0
	global_load_lds_dwordx4 v[218:219], off
	v_lshl_add_u64 v[218:219], s[50:51], 0, v[128:129]
	s_mov_b32 m0, s19
	s_nop 0
	global_load_lds_dwordx4 v[218:219], off
	s_mov_b32 m0, s59
	s_nop 0
	global_load_lds_dwordx4 v[220:221], off
	s_waitcnt vmcnt(8)
	s_waitcnt lgkmcnt(0)
	s_barrier
	s_waitcnt lgkmcnt(0)
	v_mfma_f32_16x16x32_bf16 v[60:63], v[142:145], v[180:183], v[60:63]
	v_mfma_f32_16x16x32_bf16 v[56:59], v[150:153], v[180:183], v[56:59]
	v_mfma_f32_16x16x32_bf16 v[52:55], v[142:145], v[188:191], v[52:55]
	v_mfma_f32_16x16x32_bf16 v[48:51], v[150:153], v[188:191], v[48:51]
	v_mfma_f32_16x16x32_bf16 v[36:39], v[142:145], v[196:199], v[36:39]
	v_mfma_f32_16x16x32_bf16 v[32:35], v[150:153], v[196:199], v[32:35]
	v_mfma_f32_16x16x32_bf16 v[20:23], v[142:145], v[204:207], v[20:23]
	v_mfma_f32_16x16x32_bf16 v[16:19], v[150:153], v[204:207], v[16:19]
	v_mfma_f32_16x16x32_bf16 v[60:63], v[146:149], v[184:187], v[60:63]
	v_mfma_f32_16x16x32_bf16 v[56:59], v[154:157], v[184:187], v[56:59]
	v_mfma_f32_16x16x32_bf16 v[52:55], v[146:149], v[192:195], v[52:55]
	v_mfma_f32_16x16x32_bf16 v[48:51], v[154:157], v[192:195], v[48:51]
	v_mfma_f32_16x16x32_bf16 v[36:39], v[146:149], v[200:203], v[36:39]
	v_mfma_f32_16x16x32_bf16 v[32:35], v[154:157], v[200:203], v[32:35]
	v_mfma_f32_16x16x32_bf16 v[20:23], v[146:149], v[208:211], v[20:23]
	v_mfma_f32_16x16x32_bf16 v[16:19], v[154:157], v[208:211], v[16:19]
	v_mfma_f32_16x16x32_bf16 v[44:47], v[164:167], v[180:183], v[44:47]
	v_mfma_f32_16x16x32_bf16 v[40:43], v[172:175], v[180:183], v[40:43]
	v_mfma_f32_16x16x32_bf16 v[28:31], v[164:167], v[188:191], v[28:31]
	v_mfma_f32_16x16x32_bf16 v[24:27], v[172:175], v[188:191], v[24:27]
	v_mfma_f32_16x16x32_bf16 v[12:15], v[164:167], v[196:199], v[12:15]
	v_mfma_f32_16x16x32_bf16 v[8:11], v[172:175], v[196:199], v[8:11]
	v_mfma_f32_16x16x32_bf16 v[4:7], v[164:167], v[204:207], v[4:7]
	v_mfma_f32_16x16x32_bf16 v[0:3], v[172:175], v[204:207], v[0:3]
	v_mfma_f32_16x16x32_bf16 v[44:47], v[168:171], v[184:187], v[44:47]
	v_mfma_f32_16x16x32_bf16 v[40:43], v[176:179], v[184:187], v[40:43]
	v_mfma_f32_16x16x32_bf16 v[28:31], v[168:171], v[192:195], v[28:31]
	v_mfma_f32_16x16x32_bf16 v[24:27], v[176:179], v[192:195], v[24:27]
	v_mfma_f32_16x16x32_bf16 v[12:15], v[168:171], v[200:203], v[12:15]
	v_mfma_f32_16x16x32_bf16 v[8:11], v[176:179], v[200:203], v[8:11]
	v_mfma_f32_16x16x32_bf16 v[4:7], v[168:171], v[208:211], v[4:7]
	v_mfma_f32_16x16x32_bf16 v[0:3], v[176:179], v[208:211], v[0:3]
	s_barrier
	s_add_i32 s78, 0, 0x18000
	s_add_i32 s79, 0, 0x1c000
	v_add_u32_e32 v154, s78, v160
	v_add_u32_e32 v230, s78, v233
	v_add_u32_e32 v176, s79, v160
	v_add_u32_e32 v231, s79, v233
	ds_read_b128 v[142:145], v154
	ds_read_b128 v[146:149], v230
	ds_read_b128 v[150:153], v154 offset:2048
	ds_read_b128 v[154:157], v230 offset:2048
	ds_read_b128 v[164:167], v176
	ds_read_b128 v[168:171], v231
	ds_read_b128 v[172:175], v176 offset:2048
	ds_read_b128 v[176:179], v231 offset:2048
	s_add_u32 s50, s50, 0x100000
	s_addc_u32 s51, s51, 0
	s_mov_b32 m0, s60
	v_lshl_add_u64 v[222:223], s[50:51], 0, v[128:129]
	ds_read_b128 v[180:183], v163 offset:32768
	ds_read_b128 v[184:187], v232 offset:32768
	ds_read_b128 v[188:191], v163 offset:34816
	ds_read_b128 v[192:195], v232 offset:34816
	ds_read_b128 v[196:199], v163 offset:36864
	ds_read_b128 v[200:203], v232 offset:36864
	ds_read_b128 v[204:207], v163 offset:38912
	ds_read_b128 v[208:211], v232 offset:38912
	global_load_lds_dwordx4 v[222:223], off
	v_lshl_add_u64 v[222:223], s[50:51], 0, v[130:131]
	s_mov_b32 m0, s61
	s_nop 0
	global_load_lds_dwordx4 v[222:223], off
	s_waitcnt vmcnt(8)
	s_waitcnt lgkmcnt(0)
	s_barrier
	s_waitcnt lgkmcnt(0)
	v_mfma_f32_16x16x32_bf16 v[124:127], v[142:145], v[180:183], v[124:127]
	v_mfma_f32_16x16x32_bf16 v[120:123], v[150:153], v[180:183], v[120:123]
	v_mfma_f32_16x16x32_bf16 v[116:119], v[142:145], v[188:191], v[116:119]
	v_mfma_f32_16x16x32_bf16 v[112:115], v[150:153], v[188:191], v[112:115]
	v_mfma_f32_16x16x32_bf16 v[100:103], v[142:145], v[196:199], v[100:103]
	v_mfma_f32_16x16x32_bf16 v[96:99], v[150:153], v[196:199], v[96:99]
	v_mfma_f32_16x16x32_bf16 v[84:87], v[142:145], v[204:207], v[84:87]
	v_mfma_f32_16x16x32_bf16 v[80:83], v[150:153], v[204:207], v[80:83]
	v_mfma_f32_16x16x32_bf16 v[124:127], v[146:149], v[184:187], v[124:127]
	v_mfma_f32_16x16x32_bf16 v[120:123], v[154:157], v[184:187], v[120:123]
	v_mfma_f32_16x16x32_bf16 v[116:119], v[146:149], v[192:195], v[116:119]
	v_mfma_f32_16x16x32_bf16 v[112:115], v[154:157], v[192:195], v[112:115]
	v_mfma_f32_16x16x32_bf16 v[100:103], v[146:149], v[200:203], v[100:103]
	v_mfma_f32_16x16x32_bf16 v[96:99], v[154:157], v[200:203], v[96:99]
	v_mfma_f32_16x16x32_bf16 v[84:87], v[146:149], v[208:211], v[84:87]
	v_mfma_f32_16x16x32_bf16 v[80:83], v[154:157], v[208:211], v[80:83]
	v_mfma_f32_16x16x32_bf16 v[108:111], v[164:167], v[180:183], v[108:111]
	v_mfma_f32_16x16x32_bf16 v[104:107], v[172:175], v[180:183], v[104:107]
	v_mfma_f32_16x16x32_bf16 v[92:95], v[164:167], v[188:191], v[92:95]
	v_mfma_f32_16x16x32_bf16 v[88:91], v[172:175], v[188:191], v[88:91]
	v_mfma_f32_16x16x32_bf16 v[76:79], v[164:167], v[196:199], v[76:79]
	v_mfma_f32_16x16x32_bf16 v[72:75], v[172:175], v[196:199], v[72:75]
	v_mfma_f32_16x16x32_bf16 v[68:71], v[164:167], v[204:207], v[68:71]
	v_mfma_f32_16x16x32_bf16 v[64:67], v[172:175], v[204:207], v[64:67]
	v_mfma_f32_16x16x32_bf16 v[108:111], v[168:171], v[184:187], v[108:111]
	v_mfma_f32_16x16x32_bf16 v[104:107], v[176:179], v[184:187], v[104:107]
	v_mfma_f32_16x16x32_bf16 v[92:95], v[168:171], v[192:195], v[92:95]
	v_mfma_f32_16x16x32_bf16 v[88:91], v[176:179], v[192:195], v[88:91]
	v_mfma_f32_16x16x32_bf16 v[76:79], v[168:171], v[200:203], v[76:79]
	v_mfma_f32_16x16x32_bf16 v[72:75], v[176:179], v[200:203], v[72:75]
	v_mfma_f32_16x16x32_bf16 v[68:71], v[168:171], v[208:211], v[68:71]
	v_mfma_f32_16x16x32_bf16 v[64:67], v[176:179], v[208:211], v[64:67]
	s_barrier
; #define PG8_BAR __builtin_amdgcn_s_barrier()
; template <class Epi, class Sched, bool FP8 = false>
; __device__ __forceinline__ void gemm_phase(LAS unsigned char* lds, const Gemm g, const Sched& S, const Epi& E, const int tid) {
;     ...
;         for (int t = 0; t < nt; t += 2) PG8_KBODY(t);
;     ...
;         if (wr == 0) PG8_BAR;
	s_add_i32 s50, s78, s58
	v_lshl_add_u64 v[214:215], v[214:215], 0, s[14:15]
	s_mov_b32 m0, s50
	ds_read_b128 v[180:183], v163 offset:49152
	ds_read_b128 v[184:187], v232 offset:49152
	ds_read_b128 v[188:191], v163 offset:51200
	ds_read_b128 v[192:195], v232 offset:51200
	ds_read_b128 v[196:199], v163 offset:53248
	ds_read_b128 v[200:203], v232 offset:53248
	ds_read_b128 v[204:207], v163 offset:55296
	ds_read_b128 v[208:211], v232 offset:55296
	global_load_lds_dwordx4 v[214:215], off
	s_add_i32 m0, s50, 0x2000
	s_add_u32 s48, s48, 0x100080
	v_lshl_add_u64 v[214:215], v[216:217], 0, s[14:15]
	s_addc_u32 s49, s49, 0
	s_add_i32 s50, s79, s58
	global_load_lds_dwordx4 v[214:215], off
	v_lshl_add_u64 v[214:215], s[48:49], 0, v[128:129]
	s_mov_b32 m0, s50
	s_nop 0
	global_load_lds_dwordx4 v[214:215], off
	v_lshl_add_u64 v[214:215], s[48:49], 0, v[130:131]
	s_add_i32 m0, s50, 0x2000
	s_nop 0
	global_load_lds_dwordx4 v[214:215], off
	v_lshl_add_u64 v[214:215], v[218:219], 0, s[14:15]
	s_mov_b32 m0, s66
	s_nop 0
	global_load_lds_dwordx4 v[214:215], off
	v_lshl_add_u64 v[214:215], v[220:221], 0, s[14:15]
	s_mov_b32 m0, s67
	s_nop 0
	global_load_lds_dwordx4 v[214:215], off
	s_waitcnt vmcnt(8)
	s_waitcnt lgkmcnt(0)
	s_barrier
	s_waitcnt lgkmcnt(0)
	v_mfma_f32_16x16x32_bf16 v[60:63], v[142:145], v[180:183], v[60:63]
	v_mfma_f32_16x16x32_bf16 v[56:59], v[150:153], v[180:183], v[56:59]
	v_mfma_f32_16x16x32_bf16 v[52:55], v[142:145], v[188:191], v[52:55]
	v_mfma_f32_16x16x32_bf16 v[48:51], v[150:153], v[188:191], v[48:51]
	v_mfma_f32_16x16x32_bf16 v[36:39], v[142:145], v[196:199], v[36:39]
	v_mfma_f32_16x16x32_bf16 v[32:35], v[150:153], v[196:199], v[32:35]
	v_mfma_f32_16x16x32_bf16 v[20:23], v[142:145], v[204:207], v[20:23]
	v_mfma_f32_16x16x32_bf16 v[16:19], v[150:153], v[204:207], v[16:19]
	v_mfma_f32_16x16x32_bf16 v[60:63], v[146:149], v[184:187], v[60:63]
	v_mfma_f32_16x16x32_bf16 v[56:59], v[154:157], v[184:187], v[56:59]
	v_mfma_f32_16x16x32_bf16 v[52:55], v[146:149], v[192:195], v[52:55]
	v_mfma_f32_16x16x32_bf16 v[48:51], v[154:157], v[192:195], v[48:51]
	v_mfma_f32_16x16x32_bf16 v[36:39], v[146:149], v[200:203], v[36:39]
	v_mfma_f32_16x16x32_bf16 v[32:35], v[154:157], v[200:203], v[32:35]
	v_mfma_f32_16x16x32_bf16 v[20:23], v[146:149], v[208:211], v[20:23]
	v_mfma_f32_16x16x32_bf16 v[16:19], v[154:157], v[208:211], v[16:19]
	v_mfma_f32_16x16x32_bf16 v[44:47], v[164:167], v[180:183], v[44:47]
	v_mfma_f32_16x16x32_bf16 v[40:43], v[172:175], v[180:183], v[40:43]
	v_mfma_f32_16x16x32_bf16 v[28:31], v[164:167], v[188:191], v[28:31]
	v_mfma_f32_16x16x32_bf16 v[24:27], v[172:175], v[188:191], v[24:27]
	v_mfma_f32_16x16x32_bf16 v[12:15], v[164:167], v[196:199], v[12:15]
	v_mfma_f32_16x16x32_bf16 v[8:11], v[172:175], v[196:199], v[8:11]
	v_mfma_f32_16x16x32_bf16 v[4:7], v[164:167], v[204:207], v[4:7]
	v_mfma_f32_16x16x32_bf16 v[0:3], v[172:175], v[204:207], v[0:3]
	v_mfma_f32_16x16x32_bf16 v[44:47], v[168:171], v[184:187], v[44:47]
	v_mfma_f32_16x16x32_bf16 v[40:43], v[176:179], v[184:187], v[40:43]
	v_mfma_f32_16x16x32_bf16 v[28:31], v[168:171], v[192:195], v[28:31]
	v_mfma_f32_16x16x32_bf16 v[24:27], v[176:179], v[192:195], v[24:27]
	v_mfma_f32_16x16x32_bf16 v[12:15], v[168:171], v[200:203], v[12:15]
	v_mfma_f32_16x16x32_bf16 v[8:11], v[176:179], v[200:203], v[8:11]
	v_mfma_f32_16x16x32_bf16 v[4:7], v[168:171], v[208:211], v[4:7]
	v_mfma_f32_16x16x32_bf16 v[0:3], v[176:179], v[208:211], v[0:3]
	s_barrier
	s_add_i32 s77, s77, 2
	s_add_u32 s46, s46, 0x100
	s_addc_u32 s47, s47, 0
	s_add_u32 s75, s75, 0x100
	s_addc_u32 s76, s76, 0
	s_cmp_gt_u32 s77, 61
	s_cbranch_scc0 .LBB0_101
	s_and_b64 vcc, exec, s[16:17]
	s_cbranch_vccz .LBB0_104
	s_barrier
